# layer-1 in-projection: last full unit's next-unit prefetch fetches the half unit's first K-tiles (was a dummy re-load); half-unit prologue waits skipped
# speedup vs baseline: 1.0024x; 1.0024x over previous
.LBB0_950:
	s_add_i32 s93, s93, 1
	s_mul_i32 s7, s93, s33
	s_add_i32 s7, s7, s2
	s_cmpk_lt_i32 s7, 0x300
	s_cselect_b64 s[54:55], -1, 0
	s_cmpk_gt_i32 s7, 0x2ff
	s_cbranch_scc1 .Lhalf_pf
	s_ashr_i32 s30, s7, 31
	s_lshr_b32 s30, s30, 29
	s_add_i32 s30, s7, s30
	s_ashr_i32 s31, s30, 3
	s_and_b32 s30, s30, -8
	s_sub_i32 s7, s7, s30
	s_mul_i32 s30, s7, 0x60
	s_add_i32 s30, s30, s31
	s_mul_hi_i32 s31, s30, 0x2aaaaaab
	s_lshr_b32 s50, s31, 31
	s_lshr_b32 s31, s31, 4
	s_add_i32 s31, s31, s50
	s_mulk_i32 s31, 0x60
	s_sub_i32 s30, s30, s31
	s_bfe_i32 s31, s30, 0x80000
	s_bfe_u32 s31, s31, 0x3000c
	s_mov_b64 s[26:27], s[0:1]
	s_add_i32 s31, s30, s31
	s_bfe_i32 s50, s31, 0x80000
	s_and_b32 s31, s31, 0xf8
	s_load_dwordx2 s[26:27], s[26:27], 0xa8
	s_sub_i32 s30, s30, s31
	s_lshl_b32 s7, s7, 3
	s_sext_i32_i8 s30, s30
	s_sext_i32_i16 s51, s50
	s_add_i32 s50, s7, s30
	s_lshr_b32 s56, s51, 3
	s_ashr_i32 s30, s51, 3
	s_ashr_i32 s51, s50, 31
	s_lshl_b64 s[52:53], s[50:51], 19
	s_waitcnt lgkmcnt(0)
	s_add_u32 s7, s26, s52
	s_addc_u32 s31, s27, s53
	s_ashr_i32 s52, s50, 3
	s_ashr_i32 s53, s52, 31
	s_lshl_b64 s[52:53], s[52:53], 22
	s_add_u32 s7, s7, s52
	s_addc_u32 s31, s31, s53
	s_add_u32 s52, s7, 0x1800000
	s_addc_u32 s53, s31, 0
	s_bfe_i64 s[56:57], s[56:57], 0x100000
	s_lshl_b64 s[56:57], s[56:57], 19
	s_add_u32 s7, s26, s56
	s_addc_u32 s26, s27, s57
	s_add_u32 s56, s7, 0xd00000
	s_addc_u32 s57, s26, 0
	s_branch .LBB0_952
.Lhalf_pf:
	s_cmp_lg_u32 s33, 0x100
	s_cbranch_scc1 .LBB0_952
	s_and_b32 s7, s83, 1
	s_add_i32 s7, s7, 12
	s_lshl_b32 s7, s7, 19
	s_add_u32 s52, s100, s7
	s_addc_u32 s53, s101, 0
	s_add_u32 s52, s52, 0xd00000
	s_addc_u32 s53, s53, 0
	s_lshr_b32 s26, s81, 28
	s_add_i32 s26, s2, s26
	s_ashr_i32 s26, s26, 4
	s_lshl_b32 s27, s82, 4
	s_add_i32 s26, s27, s26
	s_lshl_b32 s27, s26, 18
	s_add_u32 s56, s100, s27
	s_addc_u32 s57, s101, 0
	s_ashr_i32 s26, s26, 4
	s_lshl_b32 s26, s26, 22
	s_add_u32 s56, s56, s26
	s_addc_u32 s57, s57, 0
	s_add_u32 s56, s56, 0x1800000
	s_addc_u32 s57, s57, 0

.LBB0_1285:
	s_mov_b64 s[10:11], 0x80
	v_lshl_add_u64 v[6:7], v[6:7], 0, s[10:11]
	s_add_i32 m0, s28, 0x18000
	s_cmp_eq_u32 s33, 0x100
	s_cbranch_scc1 .Lhalf_nw0
	s_waitcnt vmcnt(2)
.Lhalf_nw0:
	s_barrier
	global_load_lds_dwordx4 v[6:7], off
	v_lshl_add_u64 v[4:5], v[4:5], 0, s[10:11]
	s_add_i32 m0, s28, 0x1a000
	s_add_i32 s62, s28, 0x8000
	global_load_lds_dwordx4 v[4:5], off
	v_lshl_add_u64 v[2:3], v[2:3], 0, s[10:11]
	s_mov_b32 m0, s62
	s_add_i32 s63, s28, 0xa000
	global_load_lds_dwordx4 v[2:3], off
	v_lshl_add_u64 v[0:1], v[0:1], 0, s[10:11]
	s_mov_b32 m0, s63
	v_ashrrev_i32_e32 v2, 6, v8
	global_load_lds_dwordx4 v[0:1], off
	v_and_b32_e32 v0, 15, v8
	v_or_b32_e32 v1, s41, v0
	v_lshlrev_b32_e32 v3, 6, v1
	v_and_b32_e32 v4, 48, v8
	s_movk_i32 s6, 0x3c0
	v_lshlrev_b32_e32 v1, 2, v1
	v_and_or_b32 v3, v3, s6, v4
	v_lshl_add_u32 v5, v2, 10, s80
	v_and_b32_e32 v1, 32, v1
	v_bitop3_b32 v1, v3, v5, v1 bitop3:0xde
	v_lshlrev_b32_e32 v3, 2, v8
	v_lshl_or_b32 v0, v0, 6, v4
	v_add_lshl_u32 v2, v2, s79, 10
	v_and_b32_e32 v3, 32, v3
	v_bitop3_b32 v91, v0, v2, v3 bitop3:0xde
	v_and_b32_e32 v2, 64, v244
	v_xor_b32_e32 v0, 1, v244
	v_add_u32_e32 v2, 64, v2
	v_cmp_lt_i32_e32 vcc, v0, v2
	s_lshl_b32 s6, s12, 2
	s_add_i32 s66, 0, 0x20400
	v_cndmask_b32_e32 v0, v244, v0, vcc
	v_lshlrev_b32_e32 v92, 2, v0
	v_xor_b32_e32 v0, 2, v244
	v_cmp_lt_i32_e32 vcc, v0, v2
	s_add_i32 s64, s66, s6
	s_lshl_b32 s6, s41, 2
	v_cndmask_b32_e32 v0, v244, v0, vcc
	v_lshlrev_b32_e32 v93, 2, v0
	v_xor_b32_e32 v0, 4, v244
	v_cmp_lt_i32_e32 vcc, v0, v2
	s_cmp_eq_u32 s33, 0x100
	s_cbranch_scc1 .Lhalf_nw1
	s_waitcnt vmcnt(4)
.Lhalf_nw1:
	s_add_i32 s67, s6, 0
	s_add_i32 s68, 0, 0x10000
	v_cndmask_b32_e32 v0, v244, v0, vcc
	v_lshlrev_b32_e32 v94, 2, v0
	v_xor_b32_e32 v0, 8, v244
	v_cmp_lt_i32_e32 vcc, v0, v2
	v_and_b32_e32 v2, 1, v12
	s_add_i32 s65, s67, 0x23600
	v_cndmask_b32_e32 v0, v244, v0, vcc
	v_lshlrev_b32_e32 v95, 2, v0
	v_lshlrev_b32_e32 v0, 14, v12
	v_and_b32_e32 v0, 0xffff8000, v0
	v_lshl_add_u32 v0, v13, 11, v0
	v_lshl_or_b32 v0, v2, 6, v0
	v_lshl_add_u32 v80, v14, 1, v0
	v_lshlrev_b32_e32 v0, 14, v9
	v_and_b32_e32 v0, 0xffff8000, v0
	v_lshl_add_u32 v0, v10, 11, v0
	v_and_b32_e32 v2, 1, v9
	v_lshl_or_b32 v0, v2, 6, v0
	s_add_i32 s66, s66, s6
	s_add_i32 s67, s67, 0x23800
	v_mov_b32_e32 v81, v75
	v_lshl_add_u32 v82, v11, 1, v0
	v_mov_b32_e32 v83, v75
	v_add_u32_e32 v96, s68, v91
	v_add_u32_e32 v97, 0, v1
	s_mov_b64 s[16:17], 0x1700000
	v_mov_b32_e32 v98, 0x358637bd
	s_mov_b32 s69, 0x800000
	s_mov_b64 s[18:19], 0x8a00000
	s_movk_i32 s70, 0x7f
	s_mov_b32 s71, 0x3e6d3388
	s_mov_b32 s34, 0x3f07dc22
	s_mov_b32 s36, 0xbf3a00e3
	s_mov_b32 s38, 0x3f35f0e3
	s_mov_b32 s40, 0xbe11a98e
	s_mov_b32 s42, 0x3e027906
	s_movk_i32 s72, 0x1080
	s_lshl_b32 s43, s43, 2
	s_mov_b32 s73, 0
	s_mov_b64 s[48:49], s[56:57]
	s_mov_b64 s[46:47], s[52:53]
	s_barrier
	s_branch .LBB0_1288
